# lambda dot products computed entirely by wave 1 during the pre-attention grid barrier (two sums handed over through LDS); on top of v170
# speedup vs baseline: 1.0052x; 1.0004x over previous
; __global__ void __launch_bounds__(NTHREADS) fwd_megakernel(Args a) {
;     ...
;         float d1 = 0.f, d2 = 0.f;
;         for (int i = 0; i < 64; ++i) { d1 += a.lq1[i] * a.lk1[i]; d2 += a.lq2[i] * a.lk2[i]; }
.LBB0_634:
	s_waitcnt vmcnt(0)
	s_waitcnt vmcnt(0)
	s_barrier
	s_cmp_lg_u64 s[92:93], 0
	s_cbranch_scc1 .Llam_pre
	v_readlane_b32 s98, v238, 40
	s_nop 3
	s_cmp_lg_u32 s98, 1
	s_cbranch_scc1 .Llam_pre
; __global__ void __launch_bounds__(NTHREADS) fwd_megakernel(Args a) {
;     ...
;         float d1 = 0.f, d2 = 0.f;
;         for (int i = 0; i < 64; ++i) { d1 += a.lq1[i] * a.lk1[i]; d2 += a.lq2[i] * a.lk2[i]; }
	v_mbcnt_lo_u32_b32 v3, -1, 0
	v_mbcnt_hi_u32_b32 v3, -1, v3
	v_lshlrev_b32_e32 v3, 2, v3
	global_load_dword v134, v3, s[80:81]
	global_load_dword v135, v3, s[82:83]
	global_load_dword v136, v3, s[52:53]
	global_load_dword v137, v3, s[54:55]
	v_mov_b32_e32 v0, 0
	v_mov_b32_e32 v1, 0
	v_mov_b32_e32 v133, 0
	s_waitcnt vmcnt(3)
	ds_write_b32 v3, v134
	s_waitcnt vmcnt(2)
	ds_write_b32 v3, v135 offset:256
	s_waitcnt vmcnt(1)
	ds_write_b32 v3, v136 offset:512
	s_waitcnt vmcnt(0)
	ds_write_b32 v3, v137 offset:768
	s_waitcnt lgkmcnt(0)
	ds_read_b128 v[4:7], v133 offset:0
	ds_read_b128 v[8:11], v133 offset:16
	ds_read_b128 v[12:15], v133 offset:32
	ds_read_b128 v[16:19], v133 offset:48
	ds_read_b128 v[20:23], v133 offset:64
	ds_read_b128 v[24:27], v133 offset:80
	ds_read_b128 v[28:31], v133 offset:96
	ds_read_b128 v[32:35], v133 offset:112
	ds_read_b128 v[36:39], v133 offset:256
	ds_read_b128 v[40:43], v133 offset:272
	ds_read_b128 v[44:47], v133 offset:288
	ds_read_b128 v[48:51], v133 offset:304
	ds_read_b128 v[52:55], v133 offset:320
	ds_read_b128 v[56:59], v133 offset:336
	ds_read_b128 v[60:63], v133 offset:352
	ds_read_b128 v[64:67], v133 offset:368
	ds_read_b128 v[68:71], v133 offset:512
	ds_read_b128 v[72:75], v133 offset:528
	ds_read_b128 v[76:79], v133 offset:544
	ds_read_b128 v[80:83], v133 offset:560
	ds_read_b128 v[84:87], v133 offset:576
	ds_read_b128 v[88:91], v133 offset:592
	ds_read_b128 v[92:95], v133 offset:608
	ds_read_b128 v[96:99], v133 offset:624
	ds_read_b128 v[100:103], v133 offset:768
	ds_read_b128 v[104:107], v133 offset:784
	ds_read_b128 v[108:111], v133 offset:800
	ds_read_b128 v[112:115], v133 offset:816
	ds_read_b128 v[116:119], v133 offset:832
	ds_read_b128 v[120:123], v133 offset:848
	ds_read_b128 v[124:127], v133 offset:864
	ds_read_b128 v[128:131], v133 offset:880
	s_waitcnt lgkmcnt(0)
	v_fma_f32 v0, v4, v36, v0
	v_fma_f32 v1, v68, v100, v1
	v_fma_f32 v0, v5, v37, v0
	v_fma_f32 v1, v69, v101, v1
	v_fma_f32 v0, v6, v38, v0
	v_fma_f32 v1, v70, v102, v1
	v_fma_f32 v0, v7, v39, v0
	v_fma_f32 v1, v71, v103, v1
	v_fma_f32 v0, v8, v40, v0
	v_fma_f32 v1, v72, v104, v1
	v_fma_f32 v0, v9, v41, v0
	v_fma_f32 v1, v73, v105, v1
	v_fma_f32 v0, v10, v42, v0
	v_fma_f32 v1, v74, v106, v1
	v_fma_f32 v0, v11, v43, v0
	v_fma_f32 v1, v75, v107, v1
	v_fma_f32 v0, v12, v44, v0
	v_fma_f32 v1, v76, v108, v1
	v_fma_f32 v0, v13, v45, v0
	v_fma_f32 v1, v77, v109, v1
	v_fma_f32 v0, v14, v46, v0
	v_fma_f32 v1, v78, v110, v1
	v_fma_f32 v0, v15, v47, v0
	v_fma_f32 v1, v79, v111, v1
	v_fma_f32 v0, v16, v48, v0
	v_fma_f32 v1, v80, v112, v1
	v_fma_f32 v0, v17, v49, v0
	v_fma_f32 v1, v81, v113, v1
	v_fma_f32 v0, v18, v50, v0
	v_fma_f32 v1, v82, v114, v1
	v_fma_f32 v0, v19, v51, v0
	v_fma_f32 v1, v83, v115, v1
	v_fma_f32 v0, v20, v52, v0
	v_fma_f32 v1, v84, v116, v1
	v_fma_f32 v0, v21, v53, v0
	v_fma_f32 v1, v85, v117, v1
	v_fma_f32 v0, v22, v54, v0
	v_fma_f32 v1, v86, v118, v1
	v_fma_f32 v0, v23, v55, v0
	v_fma_f32 v1, v87, v119, v1
	v_fma_f32 v0, v24, v56, v0
	v_fma_f32 v1, v88, v120, v1
	v_fma_f32 v0, v25, v57, v0
	v_fma_f32 v1, v89, v121, v1
	v_fma_f32 v0, v26, v58, v0
	v_fma_f32 v1, v90, v122, v1
	v_fma_f32 v0, v27, v59, v0
	v_fma_f32 v1, v91, v123, v1
	v_fma_f32 v0, v28, v60, v0
	v_fma_f32 v1, v92, v124, v1
	v_fma_f32 v0, v29, v61, v0
	v_fma_f32 v1, v93, v125, v1
	v_fma_f32 v0, v30, v62, v0
	v_fma_f32 v1, v94, v126, v1
	v_fma_f32 v0, v31, v63, v0
	v_fma_f32 v1, v95, v127, v1
	v_fma_f32 v0, v32, v64, v0
	v_fma_f32 v1, v96, v128, v1
	v_fma_f32 v0, v33, v65, v0
	v_fma_f32 v1, v97, v129, v1
	v_fma_f32 v0, v34, v66, v0
	v_fma_f32 v1, v98, v130, v1
	v_fma_f32 v0, v35, v67, v0
	v_fma_f32 v1, v99, v131, v1
	ds_read_b128 v[4:7], v133 offset:128
	ds_read_b128 v[8:11], v133 offset:144
	ds_read_b128 v[12:15], v133 offset:160
	ds_read_b128 v[16:19], v133 offset:176
	ds_read_b128 v[20:23], v133 offset:192
	ds_read_b128 v[24:27], v133 offset:208
	ds_read_b128 v[28:31], v133 offset:224
	ds_read_b128 v[32:35], v133 offset:240
	ds_read_b128 v[36:39], v133 offset:384
	ds_read_b128 v[40:43], v133 offset:400
	ds_read_b128 v[44:47], v133 offset:416
	ds_read_b128 v[48:51], v133 offset:432
	ds_read_b128 v[52:55], v133 offset:448
	ds_read_b128 v[56:59], v133 offset:464
	ds_read_b128 v[60:63], v133 offset:480
	ds_read_b128 v[64:67], v133 offset:496
	ds_read_b128 v[68:71], v133 offset:640
	ds_read_b128 v[72:75], v133 offset:656
	ds_read_b128 v[76:79], v133 offset:672
	ds_read_b128 v[80:83], v133 offset:688
	ds_read_b128 v[84:87], v133 offset:704
	ds_read_b128 v[88:91], v133 offset:720
	ds_read_b128 v[92:95], v133 offset:736
	ds_read_b128 v[96:99], v133 offset:752
	ds_read_b128 v[100:103], v133 offset:896
	ds_read_b128 v[104:107], v133 offset:912
	ds_read_b128 v[108:111], v133 offset:928
	ds_read_b128 v[112:115], v133 offset:944
	ds_read_b128 v[116:119], v133 offset:960
	ds_read_b128 v[120:123], v133 offset:976
	ds_read_b128 v[124:127], v133 offset:992
	ds_read_b128 v[128:131], v133 offset:1008
	s_waitcnt lgkmcnt(0)
	v_fma_f32 v0, v4, v36, v0
	v_fma_f32 v1, v68, v100, v1
	v_fma_f32 v0, v5, v37, v0
	v_fma_f32 v1, v69, v101, v1
	v_fma_f32 v0, v6, v38, v0
	v_fma_f32 v1, v70, v102, v1
	v_fma_f32 v0, v7, v39, v0
	v_fma_f32 v1, v71, v103, v1
	v_fma_f32 v0, v8, v40, v0
	v_fma_f32 v1, v72, v104, v1
	v_fma_f32 v0, v9, v41, v0
	v_fma_f32 v1, v73, v105, v1
	v_fma_f32 v0, v10, v42, v0
	v_fma_f32 v1, v74, v106, v1
	v_fma_f32 v0, v11, v43, v0
	v_fma_f32 v1, v75, v107, v1
	v_fma_f32 v0, v12, v44, v0
	v_fma_f32 v1, v76, v108, v1
	v_fma_f32 v0, v13, v45, v0
	v_fma_f32 v1, v77, v109, v1
	v_fma_f32 v0, v14, v46, v0
	v_fma_f32 v1, v78, v110, v1
	v_fma_f32 v0, v15, v47, v0
	v_fma_f32 v1, v79, v111, v1
	v_fma_f32 v0, v16, v48, v0
	v_fma_f32 v1, v80, v112, v1
	v_fma_f32 v0, v17, v49, v0
	v_fma_f32 v1, v81, v113, v1
	v_fma_f32 v0, v18, v50, v0
	v_fma_f32 v1, v82, v114, v1
	v_fma_f32 v0, v19, v51, v0
	v_fma_f32 v1, v83, v115, v1
	v_fma_f32 v0, v20, v52, v0
	v_fma_f32 v1, v84, v116, v1
	v_fma_f32 v0, v21, v53, v0
	v_fma_f32 v1, v85, v117, v1
	v_fma_f32 v0, v22, v54, v0
	v_fma_f32 v1, v86, v118, v1
	v_fma_f32 v0, v23, v55, v0
	v_fma_f32 v1, v87, v119, v1
	v_fma_f32 v0, v24, v56, v0
	v_fma_f32 v1, v88, v120, v1
	v_fma_f32 v0, v25, v57, v0
	v_fma_f32 v1, v89, v121, v1
	v_fma_f32 v0, v26, v58, v0
	v_fma_f32 v1, v90, v122, v1
	v_fma_f32 v0, v27, v59, v0
	v_fma_f32 v1, v91, v123, v1
	v_fma_f32 v0, v28, v60, v0
	v_fma_f32 v1, v92, v124, v1
	v_fma_f32 v0, v29, v61, v0
	v_fma_f32 v1, v93, v125, v1
	v_fma_f32 v0, v30, v62, v0
	v_fma_f32 v1, v94, v126, v1
	v_fma_f32 v0, v31, v63, v0
	v_fma_f32 v1, v95, v127, v1
	v_fma_f32 v0, v32, v64, v0
	v_fma_f32 v1, v96, v128, v1
	v_fma_f32 v0, v33, v65, v0
	v_fma_f32 v1, v97, v129, v1
	v_fma_f32 v0, v34, v66, v0
	v_fma_f32 v1, v98, v130, v1
	v_fma_f32 v0, v35, v67, v0
	v_fma_f32 v1, v99, v131, v1
	ds_write_b64 v133, v[0:1] offset:1024
	s_waitcnt lgkmcnt(0)

; __global__ void __launch_bounds__(NTHREADS) fwd_megakernel(Args a) {
;     ...
;         float d1 = 0.f, d2 = 0.f;
;         for (int i = 0; i < 64; ++i) { d1 += a.lq1[i] * a.lk1[i]; d2 += a.lq2[i] * a.lk2[i]; }
;         const float lam = expf(d1) - expf(d2) + LAM_INIT;
;         for (int u = vcu; u < NB * 8 * (SEQ / 256); u += G) {
;             const int bh = u >> 5, qb = u & 31;
;             att::attn_unit(bh >> 3, bh & 7, qb, Qb, Kb, Vb, Ob, (bf16_t*)a.out, a.subln, lam, (char*)lds);
.LBB0_687:
	v_mov_b32_e32 v133, 0
	ds_read_b64 v[0:1], v133 offset:1024
	s_waitcnt lgkmcnt(0)
	s_add_u32 s21, s30, 0xde00000
	s_addc_u32 s82, s31, 0
	s_cmpk_gt_i32 s2, 0x1ff
	s_cbranch_scc1 .LBB0_745
	v_mul_f32_e32 v2, 0x3fb8aa3b, v0
	s_mov_b32 s0, 0x3fb8aa3b
	v_rndne_f32_e32 v3, v2
	v_sub_f32_e32 v4, v2, v3
	v_fma_f32 v2, v0, s0, -v2
	v_fmac_f32_e32 v2, 0x32a5705f, v0
	v_add_f32_e32 v2, v4, v2
	v_exp_f32_e32 v2, v2
	v_cvt_i32_f32_e32 v3, v3
	s_mov_b32 s1, 0xc2ce8ed0
	v_cmp_ngt_f32_e32 vcc, s1, v0
	s_mov_b32 s4, 0x42b17218
	v_ldexp_f32 v2, v2, v3
	v_mul_f32_e32 v3, 0x3fb8aa3b, v1
	v_rndne_f32_e32 v4, v3
	v_sub_f32_e32 v5, v3, v4
	v_fma_f32 v3, v1, s0, -v3
	v_fmac_f32_e32 v3, 0x32a5705f, v1
	v_add_f32_e32 v3, v5, v3
	v_exp_f32_e32 v3, v3
	v_cvt_i32_f32_e32 v4, v4
	v_cndmask_b32_e32 v2, 0, v2, vcc
	v_mov_b32_e32 v5, 0x7f800000
	v_cmp_nlt_f32_e32 vcc, s4, v0
	s_add_u32 s16, s30, 0xbc40000
	s_mov_b32 s7, 0
	v_cndmask_b32_e32 v0, v5, v2, vcc
	v_ldexp_f32 v2, v3, v4
	v_cmp_ngt_f32_e32 vcc, s1, v1
	s_addc_u32 s17, s31, 0
	s_lshl_b32 s23, s2, 2
	v_cndmask_b32_e32 v2, 0, v2, vcc
	v_cmp_nlt_f32_e32 vcc, s4, v1
	s_lshl_b32 s46, s90, 2
	v_mov_b32_e32 v167, 0
	v_cndmask_b32_e32 v1, v5, v2, vcc
	v_sub_f32_e32 v0, v0, v1
	v_add_f32_e32 v163, 0x3e4ccccd, v0
	s_mov_b64 s[8:9], 0x20000
	s_mov_b32 s47, 0x4138aa3b
	s_mov_b64 s[10:11], 0x40000
	s_add_i32 s72, 0, 0x10000
	s_mov_b64 s[12:13], 0x20080
	v_mov_b32_e32 v165, 0x358637bd
	s_mov_b32 s73, 0xf800000
	v_mov_b32_e32 v175, 0x260
	s_mov_b32 s74, 0x3f4ccccd
	s_movk_i32 s75, 0x2000
	v_mbcnt_hi_u32_b32 v176, -1, v174
	s_branch .LBB0_691
